# combine phase: one dummy load per thread warms the 32-token tile's 512 YT rows before the serialized transposed reads
# baseline (speedup 1.0000x reference)
.LBB0_2315:
	s_lshl_b64 s[0:1], s[4:5], 1
	s_add_u32 s0, s20, s0
	s_addc_u32 s1, s21, s1
	v_mbcnt_lo_u32_b32 v254, -1, 0
	v_mbcnt_hi_u32_b32 v254, -1, v254
	v_readlane_b32 s98, v253, 3
	s_nop 1
	v_add_u32_e32 v254, s98, v254
	v_mul_lo_u32 v254, v254, s16
	v_lshlrev_b32_e32 v254, 1, v254
	global_load_dword v255, v254, s[0:1]
	v_lshl_add_u64 v[40:41], s[0:1], 0, v[2:3]
	s_mov_b64 s[22:23], -1
	v_mov_b32_e32 v42, v0
	s_and_saveexec_b64 s[20:21], s[8:9]
	s_cbranch_execz .LBB0_2323
	v_mov_b64_e32 v[42:43], v[0:1]
	s_and_saveexec_b64 s[22:23], s[10:11]
	s_cbranch_execz .LBB0_2320
	s_mov_b64 s[24:25], 0
	v_mov_b32_e32 v50, v44
	v_mov_b64_e32 v[42:43], v[0:1]

.LBB0_5042:
	s_barrier
	s_and_saveexec_b64 s[0:1], s[4:5]
	s_cbranch_execz .LBB0_5055
	s_ashr_i32 s6, s22, 7
	s_ashr_i32 s7, s6, 31
	s_lshl_b64 s[6:7], s[6:7], 22
	v_readlane_b32 s16, v253, 54
	v_readlane_b32 s17, v253, 55
	s_add_u32 s6, s16, s6
	s_addc_u32 s7, s17, s7
	s_lshl_b32 s16, s22, 6
	s_and_b32 s16, s16, 0x1fc0
	s_add_u32 s6, s6, s16
	s_addc_u32 s7, s7, 0
	v_mbcnt_lo_u32_b32 v254, -1, 0
	v_mbcnt_hi_u32_b32 v254, -1, v254
	v_readlane_b32 s98, v253, 3
	s_nop 1
	v_add_u32_e32 v254, s98, v254
	v_lshlrev_b32_e32 v254, 13, v254
	global_load_dword v255, v254, s[6:7]
	v_lshl_add_u64 v[0:1], s[6:7], 0, v[10:11]
	s_mov_b64 s[16:17], -1
	v_mov_b32_e32 v2, v8
	s_and_saveexec_b64 s[6:7], s[8:9]
	s_cbranch_execz .LBB0_5052
	v_mov_b64_e32 v[2:3], v[8:9]
	s_and_saveexec_b64 s[16:17], s[10:11]
	s_cbranch_execz .LBB0_5048
	s_mov_b64 s[18:19], 0
	v_mov_b32_e32 v4, v64
	v_mov_b64_e32 v[2:3], v[8:9]
